# post-LN modulate pass: LN gamma/beta hoisted out of the row loop, modulation loads batched behind one counted wait; attention-prep rows software-prefetched one row ahead
# speedup vs baseline: 1.0663x; 1.0102x over previous
;     ...
;     if (mn < MALL) {
;       const int b2 = mn / TALL, t2 = mn - b2 * TALL; const bool c2 = t2 < CTX;
;       const float* src = do_ln ? (c2 ? P.zctx + ((size_t)(b2 * CTX + t2)) * D : P.out + ((size_t)(b2 * SEQ + t2 - CTX)) * D)
;                                : (c2 ? P.ctx + ((size_t)(b2 * CTX + t2)) * D : P.x + ((size_t)(b2 * SEQ + t2 - CTX)) * D);
;       { typedef float f32x4n __attribute__((ext_vector_type(4))); const f32x4n t0 = __builtin_nontemporal_load((const f32x4n*)(src + lane * 4)), t1 = __builtin_nontemporal_load((const f32x4n*)(src + 256 + lane * 4)), t2 = __builtin_nontemporal_load((const f32x4n*)(src + 512 + lane * 4)), t3 = __builtin_nontemporal_load((const f32x4n*)(src + 768 + lane * 4)); nv0 = make_float4(t0[0], t0[1], t0[2], t0[3]); nv1 = make_float4(t1[0], t1[1], t1[2], t1[3]); nv2 = make_float4(t2[0], t2[1], t2[2], t2[3]); nv3 = make_float4(t3[0], t3[1], t3[2], t3[3]); }
;     }
;     float4 v0s[4];
;     if (dummy) {
; #pragma unroll
;       for (int i = 0; i < 4; ++i) v0s[i] = v[i];
;     }
;     if (do_ln) {
;       float s = 0.f;
; #pragma unroll
;       for (int i = 0; i < 4; ++i) s += v[i].x + v[i].y + v[i].z + v[i].w;
;       const float mean = wave_sum(s) * (1.f / 1024.f);
;       float q = 0.f;
; #pragma unroll
;       for (int i = 0; i < 4; ++i) { v[i].x -= mean; v[i].y -= mean; v[i].z -= mean; v[i].w -= mean; q += v[i].x * v[i].x + v[i].y * v[i].y + v[i].z * v[i].z + v[i].w * v[i].w; }
;       const float rstd = rsqrtf(wave_sum(q) * (1.f / 1024.f) + 1e-5f);
;       if (mode != 2 && lane == 0) *(float2*)(P.stats + (size_t)m * 2) = make_float2(mean, rstd);
; #pragma unroll
;       for (int i = 0; i < 4; ++i) {
;         float4 g4 = *(const float4*)(lg + i * 256 + lane * 4), b4 = *(const float4*)(lb + i * 256 + lane * 4);
;         v[i].x = v[i].x * rstd * g4.x + b4.x; v[i].y = v[i].y * rstd * g4.y + b4.y; v[i].z = v[i].z * rstd * g4.z + b4.z; v[i].w = v[i].w * rstd * g4.w + b4.w;
;       }
;     }
;     if (dummy) {
; #pragma unroll
;       for (int i = 0; i < 4; ++i) { asm volatile("" :: "v"(v[i].x), "v"(v[i].y), "v"(v[i].z), "v"(v[i].w)); v[i] = v0s[i]; }
;     }
;     if (mode == 2 || dummy) {
; #pragma unroll
;       for (int i = 0; i < 4; ++i) *(float4*)(xr + i * 256 + lane * 4) = v[i];
;     }
;     if (mode != 2) {
;       const int modrow = isctx ? 16 : b;
.LBB0_209:
	s_andn2_saveexec_b64 s[0:1], s[0:1]
	v_lshl_add_u32 v0, v4, 8, v5
	s_or_b64 exec, exec, s[0:1]
	s_waitcnt vmcnt(61)
	v_and_b32_e32 v22, 63, v1
	v_ashrrev_i32_e32 v1, 31, v0
	v_lshlrev_b64 v[0:1], 12, v[0:1]
	v_lshl_add_u64 v[0:1], v[2:3], 0, v[0:1]
	v_lshlrev_b32_e32 v96, 4, v22
	v_lshl_add_u64 v[0:1], v[0:1], 0, v[96:97]
	global_load_dwordx4 v[12:15], v[0:1], off offset:3072 nt
	global_load_dwordx4 v[8:11], v[0:1], off offset:2048 nt
	global_load_dwordx4 v[4:7], v[0:1], off offset:1024 nt
	s_nop 0
	global_load_dwordx4 v[0:3], v[0:1], off nt
	v_readlane_b32 s0, v251, 50
	v_readlane_b32 s1, v251, 51
	s_lshl_b32 s0, s0, 10
	s_ashr_i32 s1, s0, 31
	v_readlane_b32 s12, v253, 52
	s_lshl_b64 s[0:1], s[0:1], 2
	v_readlane_b32 s26, v252, 2
	v_readlane_b32 s13, v253, 53
	v_readlane_b32 s14, v253, 54
	v_readlane_b32 s15, v253, 55
	v_readlane_b32 s16, v253, 56
	v_readlane_b32 s17, v253, 57
	v_readlane_b32 s18, v253, 58
	v_readlane_b32 s19, v253, 59
	v_readlane_b32 s20, v253, 60
	v_readlane_b32 s21, v253, 61
	v_readlane_b32 s22, v253, 62
	v_readlane_b32 s23, v253, 63
	v_readlane_b32 s24, v252, 0
	v_readlane_b32 s25, v252, 1
	v_readlane_b32 s27, v252, 3
	s_add_u32 s4, s26, s0
	s_addc_u32 s5, s27, s1
	v_readlane_b32 s12, v253, 0
	v_readlane_b32 s13, v253, 1
	s_add_u32 s0, s12, s0
	s_addc_u32 s1, s13, s1
	v_lshl_add_u64 v[18:19], s[4:5], 0, v[96:97]
	v_lshl_add_u64 v[20:21], s[0:1], 0, v[96:97]
	v_lshlrev_b32_e32 v96, 3, v22
	v_lshlrev_b32_e32 v16, 2, v22
	v_cmp_eq_u32_e32 vcc, 0, v22
	s_waitcnt vmcnt(62)
	v_lshl_add_u64 v[22:23], s[66:67], 0, v[96:97]
	s_mov_b64 s[12:13], 0
	v_readlane_b32 s14, v253, 2
	v_readlane_b32 s15, v253, 3
	v_readlane_b32 s16, v253, 4
	v_readlane_b32 s17, v253, 5
	v_readlane_b32 s18, v253, 6
	v_readlane_b32 s19, v253, 7
	v_readlane_b32 s20, v253, 8
	v_readlane_b32 s21, v253, 9
	v_readlane_b32 s22, v253, 10
	v_readlane_b32 s23, v253, 11
	v_readlane_b32 s24, v253, 12
	v_readlane_b32 s25, v253, 13
	v_readlane_b32 s26, v253, 14
	v_readlane_b32 s27, v253, 15
	global_load_dwordx4 v[60:63], v[18:19], off
	global_load_dwordx4 v[64:67], v[18:19], off offset:1024
	global_load_dwordx4 v[68:71], v[18:19], off offset:2048
	global_load_dwordx4 v[72:75], v[18:19], off offset:3072
	global_load_dwordx4 v[76:79], v[20:21], off
	global_load_dwordx4 v[80:83], v[20:21], off offset:1024
	global_load_dwordx4 v[84:87], v[20:21], off offset:2048
	global_load_dwordx4 v[88:91], v[20:21], off offset:3072
	s_branch .LBB0_213
.LBB0_212:
	s_or_b64 exec, exec, s[0:1]
	v_pk_mul_f32 v[48:49], v[34:35], v[44:45] op_sel_hi:[1,0]
	v_pk_mul_f32 v[50:51], v[36:37], v[44:45] op_sel_hi:[1,0]
	v_pk_mul_f32 v[52:53], v[30:31], v[44:45] op_sel_hi:[1,0]
	v_pk_mul_f32 v[54:55], v[32:33], v[44:45] op_sel_hi:[1,0]
	v_pk_mul_f32 v[56:57], v[26:27], v[44:45] op_sel_hi:[1,0]
	v_pk_mul_f32 v[58:59], v[28:29], v[44:45] op_sel_hi:[1,0]
	v_pk_mul_f32 v[46:47], v[40:41], v[44:45] op_sel_hi:[1,0]
	v_pk_mul_f32 v[38:39], v[38:39], v[44:45] op_sel_hi:[1,0]
	v_lshlrev_b64 v[24:25], 11, v[24:25]
	s_and_b64 s[0:1], exec, s[86:87]
	s_or_b64 s[12:13], s[0:1], s[12:13]
	v_lshl_add_u64 v[40:41], v[22:23], 0, v[24:25]
	s_cmp_eq_u64 s[34:35], 0
	s_cbranch_scc1 .Lmy_p1_w1
	s_waitcnt vmcnt(5)
	s_branch .Lmy_p1_wd
.Lmy_p1_w1:
	s_waitcnt vmcnt(1)
.Lmy_p1_wd:
	v_pk_fma_f32 v[26:27], v[38:39], v[60:61], v[76:77]
	v_pk_fma_f32 v[28:29], v[46:47], v[62:63], v[78:79]
	v_pk_fma_f32 v[30:31], v[48:49], v[64:65], v[80:81]
	v_pk_fma_f32 v[32:33], v[50:51], v[66:67], v[82:83]
	v_pk_fma_f32 v[34:35], v[52:53], v[68:69], v[84:85]
	v_pk_fma_f32 v[36:37], v[54:55], v[70:71], v[86:87]
	v_pk_fma_f32 v[42:43], v[56:57], v[72:73], v[88:89]
	v_pk_fma_f32 v[44:45], v[58:59], v[74:75], v[90:91]
	v_pk_add_f32 v[114:115], v[114:115], 1.0 op_sel_hi:[1,0]
	v_pk_add_f32 v[116:117], v[116:117], 1.0 op_sel_hi:[1,0]
	v_pk_add_f32 v[118:119], v[118:119], 1.0 op_sel_hi:[1,0]
	v_pk_add_f32 v[120:121], v[120:121], 1.0 op_sel_hi:[1,0]
	v_pk_add_f32 v[122:123], v[122:123], 1.0 op_sel_hi:[1,0]
	v_pk_add_f32 v[124:125], v[124:125], 1.0 op_sel_hi:[1,0]
	v_pk_add_f32 v[126:127], v[126:127], 1.0 op_sel_hi:[1,0]
	v_pk_add_f32 v[128:129], v[128:129], 1.0 op_sel_hi:[1,0]
	v_pk_fma_f32 v[26:27], v[26:27], v[114:115], v[98:99]
	v_pk_fma_f32 v[28:29], v[28:29], v[116:117], v[100:101]
	v_pk_fma_f32 v[30:31], v[30:31], v[118:119], v[102:103]
	v_pk_fma_f32 v[32:33], v[32:33], v[120:121], v[104:105]
	v_pk_fma_f32 v[34:35], v[34:35], v[122:123], v[106:107]
	v_pk_fma_f32 v[36:37], v[36:37], v[124:125], v[108:109]
	v_pk_fma_f32 v[42:43], v[42:43], v[126:127], v[110:111]
	v_pk_fma_f32 v[44:45], v[44:45], v[128:129], v[112:113]
	v_cvt_pk_bf16_f32 v26, v26, v27
	v_cvt_pk_bf16_f32 v27, v28, v29
	v_cvt_pk_bf16_f32 v30, v30, v31
	v_cvt_pk_bf16_f32 v31, v32, v33
	v_cvt_pk_bf16_f32 v34, v34, v35
	v_cvt_pk_bf16_f32 v35, v36, v37
	v_cvt_pk_bf16_f32 v42, v42, v43
	v_cvt_pk_bf16_f32 v43, v44, v45
	global_store_dwordx2 v[40:41], v[26:27], off
	global_store_dwordx2 v[40:41], v[30:31], off offset:512
	global_store_dwordx2 v[40:41], v[34:35], off offset:1024
	global_store_dwordx2 v[40:41], v[42:43], off offset:1536
	s_andn2_b64 exec, exec, s[12:13]
	s_cbranch_execz .LBB0_223
.LBB0_213:
	s_waitcnt vmcnt(5)
	v_mov_b32_e32 v27, v13
	v_mov_b32_e32 v26, v12
	v_mov_b32_e32 v29, v15
	v_mov_b32_e32 v28, v14
	s_nop 0
	v_mov_b32_e32 v31, v9
	v_mov_b32_e32 v30, v8
	v_mov_b32_e32 v33, v11
	v_mov_b32_e32 v32, v10
	s_nop 0
	v_mov_b32_e32 v35, v5
	v_mov_b32_e32 v34, v4
	v_mov_b32_e32 v37, v7
	v_mov_b32_e32 v36, v6
	s_nop 0
	v_mov_b32_e32 v39, v1
	v_mov_b32_e32 v38, v0
	v_mov_b32_e32 v41, v3
	v_mov_b32_e32 v40, v2
	v_mov_b32_e32 v24, v17
	s_mov_b32 s88, 0x38e38e39
	v_mul_hi_i32 v92, v24, s88
	v_lshrrev_b32_e32 v93, 31, v92
	v_ashrrev_i32_e32 v92, 9, v92
	v_add_u32_e32 v92, v92, v93
	s_movk_i32 s88, 0xf700
	v_mad_i32_i24 v93, v92, s88, v24
	v_cmp_lt_i32_e64 s[90:91], s94, v93
	v_readlane_b32 s88, v251, 50
	s_mul_i32 s88, s88, 17
	v_readlane_b32 s78, v253, 24
	v_readlane_b32 s79, v253, 25
	v_cndmask_b32_e64 v92, 16, v92, s[90:91]
	v_add_u32_e32 v92, s88, v92
	v_mov_b64_e32 v[94:95], s[78:79]
	s_movk_i32 s88, 0x6000
	v_mad_i64_i32 v[94:95], s[92:93], v92, s88, v[94:95]
	v_lshlrev_b32_e32 v96, 2, v16
	v_lshl_add_u64 v[94:95], v[94:95], 0, v[96:97]
	s_mov_b64 s[78:79], 0x3000
	v_lshl_add_u64 v[92:93], v[94:95], 0, s[78:79]
	s_mov_b64 s[78:79], 0x4000
	v_lshl_add_u64 v[94:95], v[94:95], 0, s[78:79]
	global_load_dwordx4 v[98:101], v[92:93], off
	global_load_dwordx4 v[102:105], v[92:93], off offset:1024
	global_load_dwordx4 v[106:109], v[92:93], off offset:2048
	global_load_dwordx4 v[110:113], v[92:93], off offset:3072
	global_load_dwordx4 v[114:117], v[94:95], off
	global_load_dwordx4 v[118:121], v[94:95], off offset:1024
	global_load_dwordx4 v[122:125], v[94:95], off offset:2048
	global_load_dwordx4 v[126:129], v[94:95], off offset:3072
	s_mov_b64 s[76:77], 0
	s_movk_i32 s16, 0x100
	s_mov_b32 s17, 0x9000
	s_mov_b32 s18, 0x8fff
	s_mov_b32 s19, 0x38e38e39
	v_readlane_b32 s20, v251, 29
	v_readlane_b32 s21, v251, 30

; DI float bf2f(u16 v) { return __uint_as_float(((unsigned)v) << 16); }
;     ...
;   for (int m = bid * 4 + wave; m < MALL; m += nb * 4) {
;     const int b = m / TALL, t = m - b * TALL;
;     const bool isctx = t < CTX;
;     const int tp = t - CTX, rowp = tp >> 6, colp = tp & 63;
;     u16* pr = P.pbuf + (size_t)m * INW;
;     float xv[22];
; #pragma unroll
;     for (int ch = 0; ch < 22; ++ch) {
;       const int col = ch < 4 ? 960 + ch * 64 : (ch < 6 ? 1216 + (ch - 4) * 64 : (ch < 10 ? 1472 + (ch - 6) * 64 : (ch < 14 ? 1728 + (ch - 10) * 64 : (ch < 18 ? 2240 + (ch - 14) * 64 : 2496 + (ch - 18) * 64))));
;       xv[ch] = bf2f(pr[col + lane]);
;     }
;     float csA = 1.f, snA = 0.f, csD = 1.f, snD = 0.f, csR = 1.f, snR = 0.f;
;     if (!isctx) {
;       { const int e = lane & 31, pos = (lane >> 5) ? colp : rowp, i = e & 15; csA = P.ropeA[(pos * 16 + i) * 2]; snA = P.ropeA[(pos * 16 + i) * 2 + 1]; if (e < 16) snA = -snA; }
;       { const int e = lane & 15, pos = ((lane >> 4) & 1) ? colp : rowp, i = e & 7; csD = P.ropeD[(pos * 8 + i) * 2]; snD = P.ropeD[(pos * 8 + i) * 2 + 1]; if (e < 8) snD = -snD; }
;       { const int i = lane & 31; csR = P.ropeR[(tp * 32 + i) * 2]; snR = P.ropeR[(tp * 32 + i) * 2 + 1]; if (lane < 32) snR = -snR; }
;     }
;     const float gq = P.gqa_q_norm[l * 64 + lane], gk = P.gqa_k_norm[l * 64 + lane];
; #pragma unroll
;     for (int ch = 0; ch < 22; ++ch) {
;       const int col = ch < 4 ? 960 + ch * 64 : (ch < 6 ? 1216 + (ch - 4) * 64 : (ch < 10 ? 1472 + (ch - 6) * 64 : (ch < 14 ? 1728 + (ch - 10) * 64 : (ch < 18 ? 2240 + (ch - 14) * 64 : 2496 + (ch - 18) * 64))));
;       float x = xv[ch];
;       if (ch < 6) {
;         const float ss = wave_sum(x * x);
;         x = x * rsqrtf(ss * (1.f / 64.f) + 1e-6f) * (ch < 4 ? gq : gk);
;         const float partner = __shfl_xor(x, 16);
;         x = x * csA + partner * snA;
;         if (ch < 4) x *= 0.125f * LOG2E;
.LBB0_558:
	s_and_b64 vcc, exec, s[0:1]
	s_cbranch_vccz .LBB0_564
	v_mov_b32_e32 v0, v206
	v_readlane_b32 s0, v251, 23
	v_ashrrev_i32_e32 v1, 6, v0
	v_readlane_b32 s1, v251, 24
	s_waitcnt vmcnt(3)
	v_add_u32_e32 v26, s0, v1
	s_mov_b32 s0, 0x9000
	v_cmp_gt_i32_e32 vcc, s0, v26
	s_and_saveexec_b64 s[2:3], vcc
	s_cbranch_execz .LBB0_594
	v_and_b32_e32 v1, 63, v0
	v_readlane_b32 s0, v251, 50
	v_readlane_b32 s4, v253, 52
	v_readlane_b32 s8, v253, 56
	v_lshl_or_b32 v2, s0, 6, v1
	v_ashrrev_i32_e32 v3, 31, v2
	v_lshlrev_b64 v[2:3], 2, v[2:3]
	v_readlane_b32 s9, v253, 57
	v_readlane_b32 s10, v253, 58
	v_readlane_b32 s11, v253, 59
	v_lshl_add_u64 v[4:5], s[8:9], 0, v[2:3]
	global_load_dword v27, v[4:5], off
	v_lshl_add_u64 v[2:3], s[10:11], 0, v[2:3]
	global_load_dword v28, v[2:3], off
	v_readlane_b32 s5, v253, 53
	v_and_b32_e32 v2, 31, v0
	v_readlane_b32 s6, v253, 54
	v_readlane_b32 s7, v253, 55
	v_lshlrev_b32_e32 v3, 1, v0
	v_cmp_gt_u32_e64 s[4:5], 16, v2
	v_and_b32_e32 v4, 8, v0
	v_and_b32_e32 v0, 16, v0
	s_waitcnt vmcnt(4)
	v_lshlrev_b32_e32 v30, 1, v2
	v_and_b32_e32 v2, 64, v223
	v_cmp_eq_u32_e64 s[6:7], 0, v0
	v_xor_b32_e32 v0, 16, v223
	v_add_u32_e32 v2, 64, v2
	v_cmp_lt_i32_e32 vcc, v0, v2
	v_readlane_b32 s1, v251, 51
	v_and_b32_e32 v29, 30, v3
	v_cndmask_b32_e32 v0, v223, v0, vcc
	v_lshlrev_b32_e32 v31, 2, v0
	v_xor_b32_e32 v0, 8, v223
	v_cmp_lt_i32_e32 vcc, v0, v2
	v_and_b32_e32 v3, 14, v3
	v_lshlrev_b32_e32 v96, 1, v1
	v_cndmask_b32_e32 v0, v223, v0, vcc
	s_waitcnt vmcnt(3)
	v_lshlrev_b32_e32 v32, 2, v0
	v_xor_b32_e32 v0, 32, v223
	v_cmp_lt_i32_e32 vcc, v0, v2
	v_cmp_gt_u32_e64 s[0:1], 32, v1
	v_cmp_eq_u32_e64 s[8:9], 0, v4
	v_cndmask_b32_e32 v0, v223, v0, vcc
	v_lshlrev_b32_e32 v33, 2, v0
	v_lshl_add_u64 v[0:1], s[64:65], 0, v[96:97]
	s_mov_b64 s[10:11], 0
	v_lshlrev_b32_e32 v34, 2, v3
	v_readlane_b32 s12, v253, 60
	v_readlane_b32 s13, v253, 61
	v_readlane_b32 s14, v253, 62
	v_readlane_b32 s15, v253, 63
	v_readlane_b32 s16, v252, 0
	v_readlane_b32 s17, v252, 1
	v_readlane_b32 s18, v252, 2
	v_readlane_b32 s19, v252, 3
	s_movk_i32 s88, 0x1980
	v_mad_i64_i32 v[88:89], s[90:91], v26, s88, v[0:1]
	s_mov_b64 s[92:93], 0x1000
	v_lshl_add_u64 v[90:91], v[88:89], 0, s[92:93]
	global_load_ushort v65, v[88:89], off offset:1920
	global_load_ushort v66, v[88:89], off offset:2048
	global_load_ushort v67, v[88:89], off offset:2176
	global_load_ushort v68, v[88:89], off offset:2304
	global_load_ushort v69, v[88:89], off offset:2432
	global_load_ushort v70, v[88:89], off offset:2560
	global_load_ushort v71, v[88:89], off offset:2944
	global_load_ushort v72, v[88:89], off offset:3072
	global_load_ushort v73, v[88:89], off offset:3200
	global_load_ushort v74, v[88:89], off offset:3328
	global_load_ushort v75, v[88:89], off offset:3456
	global_load_ushort v76, v[88:89], off offset:3584
	global_load_ushort v77, v[88:89], off offset:3712
	global_load_ushort v78, v[88:89], off offset:3840
	global_load_ushort v79, v[90:91], off offset:384
	global_load_ushort v80, v[90:91], off offset:512
	global_load_ushort v81, v[90:91], off offset:640
	global_load_ushort v82, v[90:91], off offset:768
	global_load_ushort v83, v[90:91], off offset:896
	global_load_ushort v84, v[90:91], off offset:1024
	global_load_ushort v85, v[90:91], off offset:1152
	global_load_ushort v86, v[90:91], off offset:1280
	s_waitcnt vmcnt(0)
	s_branch .Lmy_ap_entry
.LBB0_561:
	s_or_b64 exec, exec, s[12:13]
	v_readlane_b32 s88, v251, 29
	s_nop 1
	v_add_u32_e32 v87, s88, v26
	v_min_i32_e32 v87, 0x8fff, v87
	s_movk_i32 s88, 0x1980
	v_mad_i64_i32 v[88:89], s[90:91], v87, s88, v[0:1]
	s_mov_b64 s[92:93], 0x1000
	v_lshl_add_u64 v[90:91], v[88:89], 0, s[92:93]
	global_load_ushort v65, v[88:89], off offset:1920
	global_load_ushort v66, v[88:89], off offset:2048
	global_load_ushort v67, v[88:89], off offset:2176
	global_load_ushort v68, v[88:89], off offset:2304
	global_load_ushort v69, v[88:89], off offset:2432
	global_load_ushort v70, v[88:89], off offset:2560
	global_load_ushort v71, v[88:89], off offset:2944
	global_load_ushort v72, v[88:89], off offset:3072
	global_load_ushort v73, v[88:89], off offset:3200
	global_load_ushort v74, v[88:89], off offset:3328
	global_load_ushort v75, v[88:89], off offset:3456
	global_load_ushort v76, v[88:89], off offset:3584
	global_load_ushort v77, v[88:89], off offset:3712
	global_load_ushort v78, v[88:89], off offset:3840
	global_load_ushort v79, v[90:91], off offset:384
	global_load_ushort v80, v[90:91], off offset:512
	global_load_ushort v81, v[90:91], off offset:640
	global_load_ushort v82, v[90:91], off offset:768
	global_load_ushort v83, v[90:91], off offset:896
	global_load_ushort v84, v[90:91], off offset:1024
	global_load_ushort v85, v[90:91], off offset:1152
	global_load_ushort v86, v[90:91], off offset:1280
	s_mov_b64 s[12:13], 0x1180
	s_nop 0
	v_lshlrev_b32_e32 v57, 16, v38
	v_lshl_add_u64 v[22:23], v[4:5], 0, s[12:13]
	s_mov_b64 s[12:13], 0x1200
	s_nop 0
	v_lshlrev_b32_e32 v58, 16, v39
	v_mul_f32_e32 v38, v57, v57
	v_lshl_add_u64 v[20:21], v[4:5], 0, s[12:13]
	s_mov_b64 s[12:13], 0x1280
	s_nop 0
	v_lshlrev_b32_e32 v59, 16, v40
	v_mov_b32_dpp v38, v38 quad_perm:[1,0,3,2] row_mask:0xf bank_mask:0xf bound_ctrl:1
	v_mul_f32_e32 v40, v58, v58
	v_lshl_add_u64 v[18:19], v[4:5], 0, s[12:13]
	s_mov_b64 s[12:13], 0x1300
	v_fmac_f32_e32 v38, v57, v57
	v_mov_b32_dpp v40, v40 quad_perm:[1,0,3,2] row_mask:0xf bank_mask:0xf bound_ctrl:1
	v_lshl_add_u64 v[14:15], v[4:5], 0, s[12:13]
	s_mov_b64 s[12:13], 0x1380
	v_add_f32_dpp v38, v38, v38 quad_perm:[2,3,0,1] row_mask:0xf bank_mask:0xf bound_ctrl:1
	v_fmac_f32_e32 v40, v58, v58
	v_lshl_add_u64 v[12:13], v[4:5], 0, s[12:13]
;     ...
;     for (int ch = 0; ch < 22; ++ch) {
;       const int col = ch < 4 ? 960 + ch * 64 : (ch < 6 ? 1216 + (ch - 4) * 64 : (ch < 10 ? 1472 + (ch - 6) * 64 : (ch < 14 ? 1728 + (ch - 10) * 64 : (ch < 18 ? 2240 + (ch - 14) * 64 : 2496 + (ch - 18) * 64))));
;       float x = xv[ch];
;       if (ch < 6) {
;         const float ss = wave_sum(x * x);
;         x = x * rsqrtf(ss * (1.f / 64.f) + 1e-6f) * (ch < 4 ? gq : gk);
;         const float partner = __shfl_xor(x, 16);
;         x = x * csA + partner * snA;
;         if (ch < 4) x *= 0.125f * LOG2E;
	s_mov_b64 s[12:13], 0x1400
	v_add_f32_dpp v38, v38, v38 row_half_mirror row_mask:0xf bank_mask:0xf bound_ctrl:1
	v_add_f32_dpp v40, v40, v40 quad_perm:[2,3,0,1] row_mask:0xf bank_mask:0xf bound_ctrl:1
	v_lshl_add_u64 v[10:11], v[4:5], 0, s[12:13]
	s_mov_b64 s[12:13], 0x1480
	v_add_f32_dpp v38, v38, v38 row_mirror row_mask:0xf bank_mask:0xf bound_ctrl:1
	v_add_f32_dpp v40, v40, v40 row_half_mirror row_mask:0xf bank_mask:0xf bound_ctrl:1
	v_lshl_add_u64 v[8:9], v[4:5], 0, s[12:13]
	s_mov_b64 s[12:13], 0x1500
	v_readlane_b32 s14, v38, 16
	v_readlane_b32 s15, v38, 48
	v_add_f32_dpp v40, v40, v40 row_mirror row_mask:0xf bank_mask:0xf bound_ctrl:1
	v_lshl_add_u64 v[6:7], v[4:5], 0, s[12:13]
	v_readlane_b32 s12, v38, 0
	v_readlane_b32 s13, v38, 32
	v_mov_b32_e32 v38, s14
	v_mov_b32_e32 v39, s15
	v_readlane_b32 s14, v40, 16
	v_readlane_b32 s15, v40, 48
	s_nop 0
	v_lshlrev_b32_e32 v60, 16, v41
	v_pk_add_f32 v[38:39], s[12:13], v[38:39]
	v_readlane_b32 s12, v40, 0
	v_readlane_b32 s13, v40, 32
	v_mov_b32_e32 v40, s14
	v_mov_b32_e32 v41, s15
	v_pk_add_f32 v[40:41], s[12:13], v[40:41]
	s_nop 0
	v_lshlrev_b32_e32 v61, 16, v42
	s_nop 0
	v_lshlrev_b32_e32 v62, 16, v43
	v_mov_b32_e32 v42, v40
	v_mov_b32_e32 v43, v38
	v_mov_b32_e32 v38, v41
	s_mov_b32 s12, 0x358637bd
	v_pk_add_f32 v[38:39], v[42:43], v[38:39]
	v_mov_b64_e32 v[40:41], s[12:13]
	s_mov_b32 s18, 0x3c800000
	v_pk_fma_f32 v[38:39], v[38:39], s[18:19], v[40:41] op_sel_hi:[1,0,0]
	s_mov_b32 s16, 0x800000
	v_mul_f32_e32 v42, 0x4b800000, v39
	v_cmp_gt_f32_e32 vcc, s16, v39
	s_nop 0
	v_lshlrev_b32_e32 v63, 16, v36
	s_nop 0
	v_lshlrev_b32_e32 v64, 16, v37
	v_cndmask_b32_e32 v39, v39, v42, vcc
	v_rsq_f32_e32 v39, v39
	s_movk_i32 s17, 0x7fff
	v_lshlrev_b32_e32 v44, 16, v44
	v_lshlrev_b32_e32 v45, 16, v45
	v_mul_f32_e32 v36, 0x45800000, v39
	v_cndmask_b32_e32 v36, v39, v36, vcc
	v_mul_f32_e32 v36, v36, v57
	v_mul_f32_e32 v36, v27, v36
	v_mul_f32_e32 v39, 0x4b800000, v38
	v_cmp_gt_f32_e32 vcc, s16, v38
	ds_bpermute_b32 v37, v31, v36
	v_mul_f32_e32 v36, v24, v36
	v_cndmask_b32_e32 v38, v38, v39, vcc
	v_rsq_f32_e32 v38, v38
	v_lshlrev_b32_e32 v46, 16, v46
	s_waitcnt lgkmcnt(0)
	v_fmac_f32_e32 v36, v25, v37
	v_mul_f32_e32 v36, 0x3e38aa3b, v36
	v_mul_f32_e32 v37, 0x45800000, v38
	v_cndmask_b32_e32 v37, v38, v37, vcc
	v_mul_f32_e32 v37, v37, v58
	v_mul_f32_e32 v37, v27, v37
	ds_bpermute_b32 v38, v31, v37
	v_bfe_u32 v39, v36, 16, 1
	v_add3_u32 v36, v36, v39, s17
	global_store_short_d16_hi v[4:5], v36, off offset:1920
	v_mul_f32_e32 v36, v24, v37
	s_waitcnt lgkmcnt(0)
	v_fmac_f32_e32 v36, v25, v38
	v_mul_f32_e32 v57, 0x3e38aa3b, v36
	v_mul_f32_e32 v36, v59, v59
	v_mul_f32_e32 v38, v60, v60
	v_lshlrev_b32_e32 v47, 16, v47
	v_mov_b32_dpp v36, v36 quad_perm:[1,0,3,2] row_mask:0xf bank_mask:0xf bound_ctrl:1
	v_fmac_f32_e32 v36, v59, v59
	v_mov_b32_dpp v38, v38 quad_perm:[1,0,3,2] row_mask:0xf bank_mask:0xf bound_ctrl:1
	v_fmac_f32_e32 v38, v60, v60
	v_add_f32_dpp v36, v36, v36 quad_perm:[2,3,0,1] row_mask:0xf bank_mask:0xf bound_ctrl:1
	v_lshlrev_b32_e32 v48, 16, v48
	v_add_f32_dpp v38, v38, v38 quad_perm:[2,3,0,1] row_mask:0xf bank_mask:0xf bound_ctrl:1
	v_add_f32_dpp v36, v36, v36 row_half_mirror row_mask:0xf bank_mask:0xf bound_ctrl:1
	v_lshlrev_b32_e32 v49, 16, v49
	v_add_f32_dpp v38, v38, v38 row_half_mirror row_mask:0xf bank_mask:0xf bound_ctrl:1
	v_add_f32_dpp v36, v36, v36 row_mirror row_mask:0xf bank_mask:0xf bound_ctrl:1
	v_lshlrev_b32_e32 v50, 16, v50
	v_readlane_b32 s14, v36, 16
	v_readlane_b32 s15, v36, 48
	v_add_f32_dpp v38, v38, v38 row_mirror row_mask:0xf bank_mask:0xf bound_ctrl:1
	v_readlane_b32 s12, v36, 0
	v_readlane_b32 s13, v36, 32
	v_mov_b32_e32 v36, s14
	v_mov_b32_e32 v37, s15
	v_readlane_b32 s14, v38, 16
	v_readlane_b32 s15, v38, 48
	v_pk_add_f32 v[36:37], s[12:13], v[36:37]
	v_readlane_b32 s12, v38, 0
	v_readlane_b32 s13, v38, 32
	v_mov_b32_e32 v38, s14
	v_mov_b32_e32 v39, s15
	v_pk_add_f32 v[38:39], s[12:13], v[38:39]
	v_mov_b32_e32 v43, v36
	v_mov_b32_e32 v42, v38
	v_mov_b32_e32 v36, v39
	v_pk_add_f32 v[36:37], v[42:43], v[36:37]
	v_lshlrev_b32_e32 v51, 16, v51
	v_pk_fma_f32 v[36:37], v[36:37], s[18:19], v[40:41] op_sel_hi:[1,0,0]
	v_lshlrev_b32_e32 v52, 16, v52
	v_mul_f32_e32 v38, 0x4b800000, v37
	v_cmp_gt_f32_e32 vcc, s16, v37
	v_mul_f32_e32 v39, 0x4b800000, v36
	v_lshlrev_b32_e32 v53, 16, v53
	v_cndmask_b32_e32 v37, v37, v38, vcc
	v_rsq_f32_e32 v37, v37
	v_bfe_u32 v38, v57, 16, 1
	v_add3_u32 v38, v57, v38, s17
	global_store_short_d16_hi v[4:5], v38, off offset:2048
	v_mul_f32_e32 v38, 0x45800000, v37
	v_cndmask_b32_e32 v37, v37, v38, vcc
	v_mul_f32_e32 v37, v37, v59
	v_mul_f32_e32 v37, v27, v37
	v_cmp_gt_f32_e32 vcc, s16, v36
	ds_bpermute_b32 v38, v31, v37
	v_mul_f32_e32 v37, v24, v37
	v_cndmask_b32_e32 v36, v36, v39, vcc
	v_rsq_f32_e32 v36, v36
	v_lshlrev_b32_e32 v54, 16, v54
	s_waitcnt lgkmcnt(0)
	v_fmac_f32_e32 v37, v25, v38
	v_mul_f32_e32 v37, 0x3e38aa3b, v37
	v_mul_f32_e32 v38, 0x45800000, v36
	v_cndmask_b32_e32 v36, v36, v38, vcc
	v_mul_f32_e32 v36, v36, v60
	v_mul_f32_e32 v36, v27, v36
	ds_bpermute_b32 v38, v31, v36
	v_mul_f32_e32 v36, v24, v36
	v_bfe_u32 v39, v37, 16, 1
	v_add3_u32 v37, v37, v39, s17
	global_store_short_d16_hi v[4:5], v37, off offset:2176
	s_waitcnt lgkmcnt(0)
; DI u16 f2bf(float x) { unsigned u = __float_as_uint(x); u += 0x7fffu + ((u >> 16) & 1u); return (u16)(u >> 16); }
;     ...
;     for (int ch = 0; ch < 22; ++ch) {
;       const int col = ch < 4 ? 960 + ch * 64 : (ch < 6 ? 1216 + (ch - 4) * 64 : (ch < 10 ? 1472 + (ch - 6) * 64 : (ch < 14 ? 1728 + (ch - 10) * 64 : (ch < 18 ? 2240 + (ch - 14) * 64 : 2496 + (ch - 18) * 64))));
;       float x = xv[ch];
;       if (ch < 6) {
;         const float ss = wave_sum(x * x);
;         x = x * rsqrtf(ss * (1.f / 64.f) + 1e-6f) * (ch < 4 ? gq : gk);
;         const float partner = __shfl_xor(x, 16);
;         x = x * csA + partner * snA;
;         if (ch < 4) x *= 0.125f * LOG2E;
;       } else if (ch < 14) {
;         const float partner = __shfl_xor(x, 8);
;         x = x * csD + partner * snD;
;         if (ch < 10) x *= 0.17677669529663687f * LOG2E;
;       } else {
;         const float partner = __shfl_xor(x, 32);
;         x = x * csR + partner * snR;
;         if (ch >= 18) x *= 0.125f;
;       }
;       if (dummy) { asm volatile("" :: "v"(x)); x = xv[ch]; }
;       pr[col + lane] = f2bf(x);
;     }
	v_fmac_f32_e32 v36, v25, v38
	v_mul_f32_e32 v57, 0x3e38aa3b, v36
	v_mul_f32_e32 v36, v61, v61
	v_mul_f32_e32 v38, v62, v62
	v_lshlrev_b32_e32 v55, 16, v55
	v_mov_b32_dpp v36, v36 quad_perm:[1,0,3,2] row_mask:0xf bank_mask:0xf bound_ctrl:1
	v_fmac_f32_e32 v36, v61, v61
	v_mov_b32_dpp v38, v38 quad_perm:[1,0,3,2] row_mask:0xf bank_mask:0xf bound_ctrl:1
	v_fmac_f32_e32 v38, v62, v62
	v_add_f32_dpp v36, v36, v36 quad_perm:[2,3,0,1] row_mask:0xf bank_mask:0xf bound_ctrl:1
	v_lshlrev_b32_e32 v56, 16, v56
	v_add_f32_dpp v38, v38, v38 quad_perm:[2,3,0,1] row_mask:0xf bank_mask:0xf bound_ctrl:1
	v_add_f32_dpp v36, v36, v36 row_half_mirror row_mask:0xf bank_mask:0xf bound_ctrl:1
	v_lshlrev_b32_e32 v35, 16, v35
	v_add_f32_dpp v38, v38, v38 row_half_mirror row_mask:0xf bank_mask:0xf bound_ctrl:1
	v_add_f32_dpp v36, v36, v36 row_mirror row_mask:0xf bank_mask:0xf bound_ctrl:1
	s_nop 0
	v_readlane_b32 s14, v36, 16
	v_readlane_b32 s15, v36, 48
	v_add_f32_dpp v38, v38, v38 row_mirror row_mask:0xf bank_mask:0xf bound_ctrl:1
	v_readlane_b32 s12, v36, 0
	v_readlane_b32 s13, v36, 32
	v_mov_b32_e32 v36, s14
	v_mov_b32_e32 v37, s15
	v_readlane_b32 s14, v38, 16
	v_readlane_b32 s15, v38, 48
	v_pk_add_f32 v[36:37], s[12:13], v[36:37]
	v_readlane_b32 s12, v38, 0
	v_readlane_b32 s13, v38, 32
	v_mov_b32_e32 v38, s14
	v_mov_b32_e32 v39, s15
	v_pk_add_f32 v[38:39], s[12:13], v[38:39]
	v_mov_b32_e32 v43, v36
	v_mov_b32_e32 v42, v38
	v_mov_b32_e32 v36, v39
	v_pk_add_f32 v[36:37], v[42:43], v[36:37]
	v_readlane_b32 s12, v251, 29
	v_pk_fma_f32 v[36:37], v[36:37], s[18:19], v[40:41] op_sel_hi:[1,0,0]
	v_readlane_b32 s13, v251, 30
	v_mul_f32_e32 v38, 0x4b800000, v37
	v_cmp_gt_f32_e32 vcc, s16, v37
	v_mul_f32_e32 v39, 0x4b800000, v36
	v_add_u32_e32 v26, s12, v26
	v_cndmask_b32_e32 v37, v37, v38, vcc
	v_rsq_f32_e32 v37, v37
	v_bfe_u32 v38, v57, 16, 1
	v_add3_u32 v38, v57, v38, s17
	global_store_short_d16_hi v[4:5], v38, off offset:2304
	v_mul_f32_e32 v38, 0x45800000, v37
	v_cndmask_b32_e32 v37, v37, v38, vcc
	v_cmp_gt_f32_e32 vcc, s16, v36
	v_mul_f32_e32 v37, v37, v61
	v_mul_f32_e32 v37, v28, v37
	v_cndmask_b32_e32 v36, v36, v39, vcc
	v_rsq_f32_e32 v36, v36
	ds_bpermute_b32 v38, v31, v37
	v_mul_f32_e32 v37, v24, v37
	s_mov_b32 s12, 0x8fff
	v_mul_f32_e32 v39, 0x45800000, v36
	v_cndmask_b32_e32 v36, v36, v39, vcc
	v_mul_f32_e32 v36, v36, v62
	v_mul_f32_e32 v36, v28, v36
	ds_bpermute_b32 v39, v31, v36
	v_mul_f32_e32 v24, v24, v36
	ds_bpermute_b32 v36, v32, v44
	s_waitcnt lgkmcnt(2)
	v_fmac_f32_e32 v37, v25, v38
	v_bfe_u32 v38, v37, 16, 1
	s_waitcnt lgkmcnt(1)
	v_fmac_f32_e32 v24, v25, v39
	v_bfe_u32 v25, v24, 16, 1
	v_add3_u32 v24, v24, v25, s17
	global_store_short_d16_hi v[4:5], v24, off offset:2560
	s_waitcnt lgkmcnt(0)
	v_mul_f32_e32 v24, v17, v36
	ds_bpermute_b32 v25, v32, v45
	v_fmac_f32_e32 v24, v16, v44
	v_mul_f32_e32 v24, 0x3e8293ee, v24
	v_bfe_u32 v36, v24, 16, 1
	v_add3_u32 v24, v24, v36, s17
	global_store_short_d16_hi v[4:5], v24, off offset:2944
	s_waitcnt lgkmcnt(0)
	v_mul_f32_e32 v24, v17, v25
	ds_bpermute_b32 v25, v32, v46
	v_fmac_f32_e32 v24, v16, v45
	v_mul_f32_e32 v24, 0x3e8293ee, v24
	v_bfe_u32 v36, v24, 16, 1
	v_add3_u32 v24, v24, v36, s17
	global_store_short_d16_hi v[4:5], v24, off offset:3072
	s_waitcnt lgkmcnt(0)
	v_mul_f32_e32 v24, v17, v25
	ds_bpermute_b32 v25, v32, v47
	v_fmac_f32_e32 v24, v16, v46
	v_mul_f32_e32 v24, 0x3e8293ee, v24
	v_bfe_u32 v36, v24, 16, 1
	v_add3_u32 v24, v24, v36, s17
	global_store_short_d16_hi v[4:5], v24, off offset:3200
	s_waitcnt lgkmcnt(0)
	v_mul_f32_e32 v24, v17, v25
	ds_bpermute_b32 v25, v32, v48
	v_fmac_f32_e32 v24, v16, v47
	v_mul_f32_e32 v24, 0x3e8293ee, v24
	v_bfe_u32 v36, v24, 16, 1
	v_add3_u32 v24, v24, v36, s17
	global_store_short_d16_hi v[4:5], v24, off offset:3328
	s_waitcnt lgkmcnt(0)
	v_mul_f32_e32 v24, v17, v25
	ds_bpermute_b32 v25, v32, v49
	v_fmac_f32_e32 v24, v16, v48
	v_bfe_u32 v36, v24, 16, 1
	v_add3_u32 v24, v24, v36, s17
	global_store_short_d16_hi v[4:5], v24, off offset:3456
	s_waitcnt lgkmcnt(0)
	v_mul_f32_e32 v24, v17, v25
	ds_bpermute_b32 v25, v32, v50
	v_fmac_f32_e32 v24, v16, v49
	v_bfe_u32 v36, v24, 16, 1
	v_add3_u32 v24, v24, v36, s17
	global_store_short_d16_hi v[4:5], v24, off offset:3584
	s_waitcnt lgkmcnt(0)
	v_mul_f32_e32 v24, v17, v25
	ds_bpermute_b32 v25, v32, v51
	v_fmac_f32_e32 v24, v16, v50
	v_bfe_u32 v36, v24, 16, 1
	v_add3_u32 v24, v24, v36, s17
	global_store_short_d16_hi v[4:5], v24, off offset:3712
	s_waitcnt lgkmcnt(0)
	v_mul_f32_e32 v17, v17, v25
	ds_bpermute_b32 v24, v33, v52
	v_fmac_f32_e32 v17, v16, v51
	v_bfe_u32 v16, v17, 16, 1
	v_add3_u32 v37, v37, v38, s17
	v_add3_u32 v16, v17, v16, s17
	global_store_short_d16_hi v[4:5], v37, off offset:2432
	global_store_short_d16_hi v[4:5], v16, off offset:3840
	ds_bpermute_b32 v5, v33, v53
	s_waitcnt lgkmcnt(1)
	v_mul_f32_e32 v4, v3, v24
	v_fmac_f32_e32 v4, v2, v52
	v_bfe_u32 v16, v4, 16, 1
	v_add3_u32 v4, v4, v16, s17
	global_store_short_d16_hi v[22:23], v4, off
	s_waitcnt lgkmcnt(0)
	v_mul_f32_e32 v4, v3, v5
	ds_bpermute_b32 v5, v33, v54
	v_fmac_f32_e32 v4, v2, v53
	v_bfe_u32 v16, v4, 16, 1
	v_add3_u32 v4, v4, v16, s17
	global_store_short_d16_hi v[20:21], v4, off
	s_waitcnt lgkmcnt(0)
	v_mul_f32_e32 v4, v3, v5
	ds_bpermute_b32 v5, v33, v55
	v_fmac_f32_e32 v4, v2, v54
	v_bfe_u32 v16, v4, 16, 1
	v_add3_u32 v4, v4, v16, s17
	global_store_short_d16_hi v[18:19], v4, off
	s_waitcnt lgkmcnt(0)
	v_mul_f32_e32 v4, v3, v5
	ds_bpermute_b32 v5, v33, v56
	v_fmac_f32_e32 v4, v2, v55
	v_bfe_u32 v16, v4, 16, 1
	v_add3_u32 v4, v4, v16, s17
	global_store_short_d16_hi v[14:15], v4, off
	s_waitcnt lgkmcnt(0)
	v_mul_f32_e32 v4, v3, v5
	ds_bpermute_b32 v5, v33, v35
	v_fmac_f32_e32 v4, v2, v56
	v_mul_f32_e32 v4, 0x3e000000, v4
	v_bfe_u32 v14, v4, 16, 1
	v_add3_u32 v4, v4, v14, s17
	global_store_short_d16_hi v[12:13], v4, off
	s_waitcnt lgkmcnt(0)
	v_mul_f32_e32 v4, v3, v5
	ds_bpermute_b32 v5, v33, v63
	v_fmac_f32_e32 v4, v2, v35
	v_mul_f32_e32 v4, 0x3e000000, v4
	v_bfe_u32 v12, v4, 16, 1
	v_add3_u32 v4, v4, v12, s17
	global_store_short_d16_hi v[10:11], v4, off
	s_waitcnt lgkmcnt(0)
	v_mul_f32_e32 v4, v3, v5
	ds_bpermute_b32 v5, v33, v64
	v_fmac_f32_e32 v4, v2, v63
	v_mul_f32_e32 v4, 0x3e000000, v4
	v_bfe_u32 v10, v4, 16, 1
	v_cmp_lt_i32_e32 vcc, s12, v26
	s_waitcnt lgkmcnt(0)
	v_mul_f32_e32 v3, v3, v5
	v_fmac_f32_e32 v3, v2, v64
	v_mul_f32_e32 v2, 0x3e000000, v3
	v_bfe_u32 v3, v2, 16, 1
	v_add3_u32 v4, v4, v10, s17
	v_add3_u32 v2, v2, v3, s17
	s_or_b64 s[10:11], vcc, s[10:11]
	global_store_short_d16_hi v[8:9], v4, off
	global_store_short_d16_hi v[6:7], v2, off
	s_andn2_b64 exec, exec, s[10:11]
	s_cbranch_execz .LBB0_594
; DI float bf2f(u16 v) { return __uint_as_float(((unsigned)v) << 16); }
;     ...
;     const int b = m / TALL, t = m - b * TALL;
;     const bool isctx = t < CTX;
;     const int tp = t - CTX, rowp = tp >> 6, colp = tp & 63;
;     u16* pr = P.pbuf + (size_t)m * INW;
;     float xv[22];
; #pragma unroll
;     for (int ch = 0; ch < 22; ++ch) {
;       const int col = ch < 4 ? 960 + ch * 64 : (ch < 6 ? 1216 + (ch - 4) * 64 : (ch < 10 ? 1472 + (ch - 6) * 64 : (ch < 14 ? 1728 + (ch - 10) * 64 : (ch < 18 ? 2240 + (ch - 14) * 64 : 2496 + (ch - 18) * 64))));
;       xv[ch] = bf2f(pr[col + lane]);
;     }
;     float csA = 1.f, snA = 0.f, csD = 1.f, snD = 0.f, csR = 1.f, snR = 0.f;
;     if (!isctx) {
;       { const int e = lane & 31, pos = (lane >> 5) ? colp : rowp, i = e & 15; csA = P.ropeA[(pos * 16 + i) * 2]; snA = P.ropeA[(pos * 16 + i) * 2 + 1]; if (e < 16) snA = -snA; }
;       { const int e = lane & 15, pos = ((lane >> 4) & 1) ? colp : rowp, i = e & 7; csD = P.ropeD[(pos * 8 + i) * 2]; snD = P.ropeD[(pos * 8 + i) * 2 + 1]; if (e < 8) snD = -snD; }
;       { const int i = lane & 31; csR = P.ropeR[(tp * 32 + i) * 2]; snR = P.ropeR[(tp * 32 + i) * 2 + 1]; if (lane < 32) snR = -snR; }
;     }
.LBB0_562:
	s_waitcnt vmcnt(22)
.Lmy_ap_entry:
	v_mov_b32_e32 v38, v65
	v_mov_b32_e32 v39, v66
	v_mov_b32_e32 v40, v67
	v_mov_b32_e32 v41, v68
	v_mov_b32_e32 v42, v69
	v_mov_b32_e32 v43, v70
	v_mov_b32_e32 v44, v71
	v_mov_b32_e32 v45, v72
	v_mov_b32_e32 v46, v73
	v_mov_b32_e32 v47, v74
	v_mov_b32_e32 v48, v75
	v_mov_b32_e32 v49, v76
	v_mov_b32_e32 v50, v77
	v_mov_b32_e32 v51, v78
	v_mov_b32_e32 v52, v79
	v_mov_b32_e32 v53, v80
	v_mov_b32_e32 v54, v81
	v_mov_b32_e32 v55, v82
	v_mov_b32_e32 v56, v83
	v_mov_b32_e32 v35, v84
	v_mov_b32_e32 v36, v85
	v_mov_b32_e32 v37, v86
	s_movk_i32 s12, 0x1980
	v_mad_i64_i32 v[4:5], s[12:13], v26, s12, v[0:1]
	s_movk_i32 s12, 0x1000
	s_nop 0
	v_add_co_u32_e32 v2, vcc, s12, v4
	v_addc_co_u32_e32 v3, vcc, 0, v5, vcc
	s_mov_b32 s12, 0x38e38e39
	v_mul_hi_i32 v2, v26, s12
	v_lshrrev_b32_e32 v3, 31, v2
	v_ashrrev_i32_e32 v2, 9, v2
	v_add_u32_e32 v2, v2, v3
	v_mul_i32_i24_e32 v2, 0x900, v2
	v_sub_u32_e32 v6, v26, v2
	v_cmp_lt_i32_e32 vcc, s94, v6
	v_mov_b32_e32 v2, 1.0
	v_mov_b32_e32 v3, 0
	v_mov_b32_e32 v17, 0
	v_mov_b32_e32 v16, 1.0
	v_mov_b32_e32 v25, 0
	v_mov_b32_e32 v24, 1.0
	s_and_saveexec_b64 s[12:13], vcc
	s_cbranch_execz .LBB0_561
	v_add_u32_e32 v7, 0xffffff00, v6
	v_lshrrev_b32_e32 v8, 6, v7
	v_and_b32_e32 v6, 63, v6
	v_cndmask_b32_e64 v2, v6, v8, s[0:1]
	v_readlane_b32 s16, v253, 20
	v_lshl_or_b32 v96, v2, 5, v29
	v_readlane_b32 s22, v253, 26
	v_readlane_b32 s23, v253, 27
	v_readlane_b32 s24, v253, 28
	v_readlane_b32 s25, v253, 29
	v_lshl_add_u64 v[2:3], v[96:97], 2, s[22:23]
	global_load_dwordx2 v[24:25], v[2:3], off
	v_cndmask_b32_e64 v2, v6, v8, s[6:7]
	v_readlane_b32 s26, v253, 30
	v_readlane_b32 s27, v253, 31
	v_lshl_or_b32 v2, v2, 6, v34
	v_lshl_or_b32 v96, v7, 6, v30
	global_load_dwordx2 v[16:17], v2, s[24:25]
	v_lshl_add_u64 v[2:3], v[96:97], 2, s[26:27]
	global_load_dwordx2 v[2:3], v[2:3], off
	v_readlane_b32 s17, v253, 21
	v_readlane_b32 s18, v253, 22
	v_readlane_b32 s19, v253, 23
	v_readlane_b32 s20, v253, 24
	v_readlane_b32 s21, v253, 25
	v_readlane_b32 s28, v253, 32
	v_readlane_b32 s29, v253, 33
	v_readlane_b32 s30, v253, 34
	v_readlane_b32 s31, v253, 35
	s_waitcnt vmcnt(2)
	v_cndmask_b32_e64 v25, v25, -v25, s[4:5]
	s_waitcnt vmcnt(1)
	v_cndmask_b32_e64 v17, v17, -v17, s[8:9]
	s_waitcnt vmcnt(0)
	v_cndmask_b32_e64 v3, v3, -v3, s[0:1]
	s_branch .LBB0_561
